# nt on the P1 (Z, 406 MB) and P6 (hidden, 277 MB) GEMM epilogue stores
# baseline (speedup 1.0000x reference)
; __device__ __forceinline__ unsigned cvt_pk_bf16(float lo, float hi) { unsigned r; asm volatile("v_cvt_pk_bf16_f32 %0, %1, %2" : "=v"(r) : "v"(lo), "v"(hi)); return r; }
;     __device__ __forceinline__ void operator()(const f32x4 (&acc)[2][2][4][2], const Unit& u, int wr, int wc, int fr, int fq) const {
;         const int row0 = u.pm * BM + wr * 64 + fr, col0 = u.pn * BM + wc * 32 + 8 * fq;
; #pragma unroll
;         for (int ai = 0; ai < 2; ++ai)
; #pragma unroll
;             for (int m = 0; m < 4; ++m) { const int row = row0 + ai * HALF + m * 16; const float rs = ACT == 1 ? ss[row] : 1.0f;
;                 bf16_t* rowp = O + (size_t)row * ldc + col0;
; #pragma unroll
;                 for (int bj = 0; bj < 2; ++bj) { f32x4 v0 = acc[ai][bj][m][0] * rs, v1 = acc[ai][bj][m][1] * rs;
;                     if (ACT == 1) {
; #pragma unroll
;                         for (int e = 0; e < 4; ++e) { const float a0 = fmaxf(v0[e], 0.f), a1 = fmaxf(v1[e], 0.f); v0[e] = a0 * a0; v1[e] = a1 * a1; } }
;                     u32x4 w; w.x = cvt_pk_bf16(v0[0], v0[1]); w.y = cvt_pk_bf16(v0[2], v0[3]); w.z = cvt_pk_bf16(v1[0], v1[1]); w.w = cvt_pk_bf16(v1[2], v1[3]);
;                     *(u32x4*)(rowp + bj * HALF) = w; } }
.LBB0_179:
	v_lshl_or_b32 v146, s48, 8, v151
	v_lshl_add_u32 v155, s24, 8, v149
	v_ashrrev_i32_e32 v147, 31, v146
	v_mov_b64_e32 v[144:145], s[74:75]
	v_mad_i64_i32 v[156:157], s[26:27], v155, s47, v[144:145]
	v_lshlrev_b64 v[146:147], 1, v[146:147]
	v_lshl_add_u64 v[156:157], v[156:157], 0, v[146:147]
	v_cvt_pk_bf16_f32 v124, v124, v125
	v_cvt_pk_bf16_f32 v125, v126, v127
	v_cvt_pk_bf16_f32 v126, v120, v121
	v_cvt_pk_bf16_f32 v127, v122, v123
	global_store_dwordx4 v[156:157], v[124:127], off nt
	v_cvt_pk_bf16_f32 v112, v112, v113
	v_cvt_pk_bf16_f32 v113, v114, v115
	v_cvt_pk_bf16_f32 v114, v104, v105
	v_or_b32_e32 v104, 16, v155
	v_mad_i64_i32 v[104:105], s[26:27], v104, s47, v[144:145]
	v_cvt_pk_bf16_f32 v115, v106, v107
	global_store_dwordx4 v[156:157], v[112:115], off offset:256 nt
	s_andn2_b64 vcc, exec, s[4:5]
	s_mov_b64 s[4:5], -1
	v_lshl_add_u64 v[112:113], v[104:105], 0, v[146:147]
	v_cvt_pk_bf16_f32 v104, v116, v117
	v_cvt_pk_bf16_f32 v105, v118, v119
	v_cvt_pk_bf16_f32 v106, v108, v109
	v_cvt_pk_bf16_f32 v107, v110, v111
	global_store_dwordx4 v[112:113], v[104:107], off nt
	v_cvt_pk_bf16_f32 v96, v96, v97
	v_cvt_pk_bf16_f32 v97, v98, v99
	v_cvt_pk_bf16_f32 v98, v88, v89
	v_or_b32_e32 v88, 32, v155
	v_mad_i64_i32 v[88:89], s[26:27], v88, s47, v[144:145]
	v_cvt_pk_bf16_f32 v99, v90, v91
	global_store_dwordx4 v[112:113], v[96:99], off offset:256 nt
	s_nop 1
	v_lshl_add_u64 v[96:97], v[88:89], 0, v[146:147]
	v_cvt_pk_bf16_f32 v88, v100, v101
	v_cvt_pk_bf16_f32 v89, v102, v103
	v_cvt_pk_bf16_f32 v90, v92, v93
	v_cvt_pk_bf16_f32 v91, v94, v95
	global_store_dwordx4 v[96:97], v[88:91], off nt
	v_cvt_pk_bf16_f32 v80, v80, v81
	v_cvt_pk_bf16_f32 v81, v82, v83
	v_cvt_pk_bf16_f32 v82, v72, v73
	v_or_b32_e32 v72, 48, v155
	v_mad_i64_i32 v[72:73], s[26:27], v72, s47, v[144:145]
	v_cvt_pk_bf16_f32 v83, v74, v75
	global_store_dwordx4 v[96:97], v[80:83], off offset:256 nt
	s_nop 1
	v_lshl_add_u64 v[80:81], v[72:73], 0, v[146:147]
	v_cvt_pk_bf16_f32 v72, v84, v85
	v_cvt_pk_bf16_f32 v73, v86, v87
	v_cvt_pk_bf16_f32 v74, v76, v77
	v_cvt_pk_bf16_f32 v75, v78, v79
	global_store_dwordx4 v[80:81], v[72:75], off nt
	v_cvt_pk_bf16_f32 v68, v68, v69
	v_cvt_pk_bf16_f32 v69, v70, v71
	v_cvt_pk_bf16_f32 v70, v64, v65
	v_add_u32_e32 v64, 0x80, v155
	v_mad_i64_i32 v[64:65], s[26:27], v64, s47, v[144:145]
	v_lshl_add_u64 v[64:65], v[64:65], 0, v[146:147]
	v_cvt_pk_bf16_f32 v71, v66, v67
	global_store_dwordx4 v[80:81], v[68:71], off offset:256 nt
	v_cvt_pk_bf16_f32 v60, v60, v61
	v_cvt_pk_bf16_f32 v61, v62, v63
	v_cvt_pk_bf16_f32 v62, v56, v57
	v_cvt_pk_bf16_f32 v63, v58, v59
	global_store_dwordx4 v[64:65], v[60:63], off nt
	v_cvt_pk_bf16_f32 v48, v48, v49
	v_cvt_pk_bf16_f32 v49, v50, v51
	v_cvt_pk_bf16_f32 v50, v40, v41
	v_add_u32_e32 v40, 0x90, v155
	v_mad_i64_i32 v[40:41], s[26:27], v40, s47, v[144:145]
	v_cvt_pk_bf16_f32 v51, v42, v43
	global_store_dwordx4 v[64:65], v[48:51], off offset:256 nt
	s_nop 1
	v_lshl_add_u64 v[48:49], v[40:41], 0, v[146:147]
	v_cvt_pk_bf16_f32 v40, v52, v53
	v_cvt_pk_bf16_f32 v41, v54, v55
	v_cvt_pk_bf16_f32 v42, v44, v45
	v_cvt_pk_bf16_f32 v43, v46, v47
	global_store_dwordx4 v[48:49], v[40:43], off nt
	v_cvt_pk_bf16_f32 v32, v32, v33
	v_cvt_pk_bf16_f32 v33, v34, v35
	v_cvt_pk_bf16_f32 v34, v24, v25
	v_add_u32_e32 v24, 0xa0, v155
	v_mad_i64_i32 v[24:25], s[26:27], v24, s47, v[144:145]
	v_cvt_pk_bf16_f32 v35, v26, v27
	global_store_dwordx4 v[48:49], v[32:35], off offset:256 nt
	s_nop 1
	v_lshl_add_u64 v[32:33], v[24:25], 0, v[146:147]
	v_cvt_pk_bf16_f32 v24, v36, v37
	v_cvt_pk_bf16_f32 v25, v38, v39
	v_cvt_pk_bf16_f32 v26, v28, v29
	v_cvt_pk_bf16_f32 v27, v30, v31
	global_store_dwordx4 v[32:33], v[24:27], off nt
	v_cvt_pk_bf16_f32 v16, v16, v17
	v_cvt_pk_bf16_f32 v17, v18, v19
	v_cvt_pk_bf16_f32 v18, v8, v9
	v_add_u32_e32 v8, 0xb0, v155
	v_mad_i64_i32 v[8:9], s[26:27], v8, s47, v[144:145]
	v_cvt_pk_bf16_f32 v19, v10, v11
	global_store_dwordx4 v[32:33], v[16:19], off offset:256 nt
	s_nop 1
	v_lshl_add_u64 v[16:17], v[8:9], 0, v[146:147]
	v_cvt_pk_bf16_f32 v8, v20, v21
	v_cvt_pk_bf16_f32 v9, v22, v23
	v_cvt_pk_bf16_f32 v10, v12, v13
	v_cvt_pk_bf16_f32 v11, v14, v15
	global_store_dwordx4 v[16:17], v[8:11], off nt
	v_cvt_pk_bf16_f32 v4, v4, v5
	v_cvt_pk_bf16_f32 v5, v6, v7
	v_cvt_pk_bf16_f32 v6, v0, v1
	v_cvt_pk_bf16_f32 v7, v2, v3
	global_store_dwordx4 v[16:17], v[4:7], off offset:256 nt
	s_cbranch_vccnz .LBB0_168
	s_andn2_b64 vcc, exec, s[6:7]
	s_cbranch_vccnz .LBB0_167
	s_barrier
	s_branch .LBB0_167

; __device__ __forceinline__ unsigned cvt_pk_bf16(float lo, float hi) { unsigned r; asm volatile("v_cvt_pk_bf16_f32 %0, %1, %2" : "=v"(r) : "v"(lo), "v"(hi)); return r; }
;     __device__ __forceinline__ void operator()(const f32x4 (&acc)[2][2][4][2], const Unit& u, int wr, int wc, int fr, int fq) const {
;     ...
;             for (int m = 0; m < 4; ++m) { const int row = row0 + ai * HALF + m * 16; const float rs = ACT == 1 ? ss[row] : 1.0f;
;                 bf16_t* rowp = O + (size_t)row * ldc + col0;
; #pragma unroll
;                 for (int bj = 0; bj < 2; ++bj) { f32x4 v0 = acc[ai][bj][m][0] * rs, v1 = acc[ai][bj][m][1] * rs;
;                     if (ACT == 1) {
; #pragma unroll
;                         for (int e = 0; e < 4; ++e) { const float a0 = fmaxf(v0[e], 0.f), a1 = fmaxf(v1[e], 0.f); v0[e] = a0 * a0; v1[e] = a1 * a1; } }
;                     u32x4 w; w.x = cvt_pk_bf16(v0[0], v0[1]); w.y = cvt_pk_bf16(v0[2], v0[3]); w.z = cvt_pk_bf16(v1[0], v1[1]); w.w = cvt_pk_bf16(v1[2], v1[3]);
;                     *(u32x4*)(rowp + bj * HALF) = w; } }
.LBB0_936:
	v_lshl_add_u32 v148, s0, 8, v152
	v_ashrrev_i32_e32 v149, 31, v148
	v_lshl_add_u64 v[146:147], v[148:149], 2, s[86:87]
	global_load_dword v158, v[146:147], off
	v_lshl_or_b32 v144, s1, 8, v154
	v_ashrrev_i32_e32 v145, 31, v144
	v_lshlrev_b64 v[160:161], 14, v[148:149]
	v_lshlrev_b64 v[150:151], 1, v[144:145]
	v_lshl_add_u64 v[144:145], s[74:75], 0, v[160:161]
	v_lshl_add_u64 v[144:145], v[144:145], 0, v[150:151]
	s_waitcnt vmcnt(0)
	v_pk_mul_f32 v[126:127], v[126:127], v[158:159] op_sel_hi:[1,0]
	v_pk_mul_f32 v[124:125], v[124:125], v[158:159] op_sel_hi:[1,0]
	v_pk_mul_f32 v[122:123], v[122:123], v[158:159] op_sel_hi:[1,0]
	v_pk_mul_f32 v[120:121], v[120:121], v[158:159] op_sel_hi:[1,0]
	v_pk_mul_f32 v[114:115], v[114:115], v[158:159] op_sel_hi:[1,0]
	v_pk_mul_f32 v[112:113], v[112:113], v[158:159] op_sel_hi:[1,0]
	v_pk_mul_f32 v[118:119], v[118:119], v[158:159] op_sel_hi:[1,0]
	v_pk_mul_f32 v[116:117], v[116:117], v[158:159] op_sel_hi:[1,0]
	v_max_f32_e32 v124, 0, v124
	v_max_f32_e32 v120, 0, v120
	v_max_f32_e32 v125, 0, v125
	v_max_f32_e32 v121, 0, v121
	v_max_f32_e32 v126, 0, v126
	v_max_f32_e32 v122, 0, v122
	v_max_f32_e32 v127, 0, v127
	v_max_f32_e32 v123, 0, v123
	v_max_f32_e32 v112, 0, v112
	v_max_f32_e32 v113, 0, v113
	v_max_f32_e32 v114, 0, v114
	v_max_f32_e32 v115, 0, v115
	v_max_f32_e32 v116, 0, v116
	v_max_f32_e32 v117, 0, v117
	v_max_f32_e32 v118, 0, v118
	v_max_f32_e32 v119, 0, v119
	v_mul_f32_e32 v124, v124, v124
	v_mul_f32_e32 v120, v120, v120
	v_mul_f32_e32 v125, v125, v125
	v_mul_f32_e32 v121, v121, v121
	v_mul_f32_e32 v126, v126, v126
	v_mul_f32_e32 v122, v122, v122
	v_mul_f32_e32 v127, v127, v127
	v_mul_f32_e32 v123, v123, v123
	v_mul_f32_e32 v149, v112, v112
	v_mul_f32_e32 v158, v113, v113
	v_mul_f32_e32 v159, v114, v114
	v_mul_f32_e32 v160, v115, v115
	v_cvt_pk_bf16_f32 v112, v124, v125
	v_cvt_pk_bf16_f32 v113, v126, v127
	v_cvt_pk_bf16_f32 v114, v120, v121
	v_cvt_pk_bf16_f32 v115, v122, v123
	v_mul_f32_e32 v116, v116, v116
	v_mul_f32_e32 v117, v117, v117
	v_mul_f32_e32 v118, v118, v118
	v_mul_f32_e32 v119, v119, v119
	global_store_dwordx4 v[144:145], v[112:115], off nt
	s_nop 1
	v_cvt_pk_bf16_f32 v112, v116, v117
	v_cvt_pk_bf16_f32 v113, v118, v119
	v_cvt_pk_bf16_f32 v114, v149, v158
	v_cvt_pk_bf16_f32 v115, v159, v160
	global_store_dwordx4 v[144:145], v[112:115], off offset:256 nt
	global_load_dword v112, v[146:147], off offset:64
	s_waitcnt vmcnt(0)
	v_pk_mul_f32 v[110:111], v[110:111], v[112:113] op_sel_hi:[1,0]
	v_or_b32_e32 v114, 16, v148
	v_ashrrev_i32_e32 v115, 31, v114
	v_lshlrev_b64 v[114:115], 14, v[114:115]
	v_pk_mul_f32 v[108:109], v[108:109], v[112:113] op_sel_hi:[1,0]
	v_pk_mul_f32 v[106:107], v[106:107], v[112:113] op_sel_hi:[1,0]
	v_pk_mul_f32 v[104:105], v[104:105], v[112:113] op_sel_hi:[1,0]
	v_pk_mul_f32 v[98:99], v[98:99], v[112:113] op_sel_hi:[1,0]
	v_pk_mul_f32 v[96:97], v[96:97], v[112:113] op_sel_hi:[1,0]
	v_lshl_add_u64 v[114:115], s[74:75], 0, v[114:115]
	v_pk_mul_f32 v[102:103], v[102:103], v[112:113] op_sel_hi:[1,0]
	v_pk_mul_f32 v[100:101], v[100:101], v[112:113] op_sel_hi:[1,0]
	v_max_f32_e32 v108, 0, v108
	v_max_f32_e32 v104, 0, v104
	v_max_f32_e32 v109, 0, v109
	v_max_f32_e32 v105, 0, v105
	v_max_f32_e32 v110, 0, v110
	v_max_f32_e32 v106, 0, v106
	v_max_f32_e32 v111, 0, v111
	v_max_f32_e32 v107, 0, v107
	v_max_f32_e32 v96, 0, v96
	v_max_f32_e32 v97, 0, v97
	v_max_f32_e32 v98, 0, v98
	v_max_f32_e32 v99, 0, v99
	v_lshl_add_u64 v[114:115], v[114:115], 0, v[150:151]
	v_max_f32_e32 v100, 0, v100
	v_max_f32_e32 v101, 0, v101
	v_max_f32_e32 v102, 0, v102
	v_max_f32_e32 v103, 0, v103
	v_mul_f32_e32 v108, v108, v108
	v_mul_f32_e32 v104, v104, v104
	v_mul_f32_e32 v109, v109, v109
	v_mul_f32_e32 v105, v105, v105
	v_mul_f32_e32 v110, v110, v110
	v_mul_f32_e32 v106, v106, v106
	v_mul_f32_e32 v111, v111, v111
	v_mul_f32_e32 v107, v107, v107
	v_mul_f32_e32 v112, v96, v96
	v_mul_f32_e32 v113, v97, v97
	v_mul_f32_e32 v116, v98, v98
	v_mul_f32_e32 v117, v99, v99
	v_cvt_pk_bf16_f32 v96, v108, v109
	v_cvt_pk_bf16_f32 v97, v110, v111
	v_cvt_pk_bf16_f32 v98, v104, v105
	v_cvt_pk_bf16_f32 v99, v106, v107
	v_mul_f32_e32 v100, v100, v100
	v_mul_f32_e32 v101, v101, v101
	v_mul_f32_e32 v102, v102, v102
	v_mul_f32_e32 v103, v103, v103
	global_store_dwordx4 v[114:115], v[96:99], off nt
	s_nop 1
	v_cvt_pk_bf16_f32 v96, v100, v101
	v_cvt_pk_bf16_f32 v97, v102, v103
	v_cvt_pk_bf16_f32 v98, v112, v113
	v_cvt_pk_bf16_f32 v99, v116, v117
	global_store_dwordx4 v[114:115], v[96:99], off offset:256 nt
	global_load_dword v96, v[146:147], off offset:128
	s_waitcnt vmcnt(0)
	v_pk_mul_f32 v[94:95], v[94:95], v[96:97] op_sel_hi:[1,0]
	v_or_b32_e32 v98, 32, v148
	v_ashrrev_i32_e32 v99, 31, v98
	v_lshlrev_b64 v[98:99], 14, v[98:99]
	v_pk_mul_f32 v[92:93], v[92:93], v[96:97] op_sel_hi:[1,0]
	v_pk_mul_f32 v[90:91], v[90:91], v[96:97] op_sel_hi:[1,0]
	v_pk_mul_f32 v[88:89], v[88:89], v[96:97] op_sel_hi:[1,0]
	v_pk_mul_f32 v[82:83], v[82:83], v[96:97] op_sel_hi:[1,0]
	v_pk_mul_f32 v[80:81], v[80:81], v[96:97] op_sel_hi:[1,0]
	v_lshl_add_u64 v[98:99], s[74:75], 0, v[98:99]
	v_pk_mul_f32 v[86:87], v[86:87], v[96:97] op_sel_hi:[1,0]
	v_pk_mul_f32 v[84:85], v[84:85], v[96:97] op_sel_hi:[1,0]
	v_max_f32_e32 v92, 0, v92
	v_max_f32_e32 v88, 0, v88
	v_max_f32_e32 v93, 0, v93
	v_max_f32_e32 v89, 0, v89
	v_max_f32_e32 v94, 0, v94
	v_max_f32_e32 v90, 0, v90
	v_max_f32_e32 v95, 0, v95
	v_max_f32_e32 v91, 0, v91
	v_max_f32_e32 v80, 0, v80
	v_max_f32_e32 v81, 0, v81
	v_max_f32_e32 v82, 0, v82
	v_max_f32_e32 v83, 0, v83
	v_lshl_add_u64 v[98:99], v[98:99], 0, v[150:151]
	v_max_f32_e32 v84, 0, v84
	v_max_f32_e32 v85, 0, v85
	v_max_f32_e32 v86, 0, v86
	v_max_f32_e32 v87, 0, v87
	v_mul_f32_e32 v92, v92, v92
	v_mul_f32_e32 v88, v88, v88
	v_mul_f32_e32 v93, v93, v93
	v_mul_f32_e32 v89, v89, v89
	v_mul_f32_e32 v94, v94, v94
	v_mul_f32_e32 v90, v90, v90
	v_mul_f32_e32 v95, v95, v95
	v_mul_f32_e32 v91, v91, v91
	v_mul_f32_e32 v96, v80, v80
	v_mul_f32_e32 v97, v81, v81
	v_mul_f32_e32 v100, v82, v82
	v_mul_f32_e32 v101, v83, v83
	v_cvt_pk_bf16_f32 v80, v92, v93
	v_cvt_pk_bf16_f32 v81, v94, v95
	v_cvt_pk_bf16_f32 v82, v88, v89
	v_cvt_pk_bf16_f32 v83, v90, v91
	v_mul_f32_e32 v84, v84, v84
	v_mul_f32_e32 v85, v85, v85
	v_mul_f32_e32 v86, v86, v86
	v_mul_f32_e32 v87, v87, v87
	global_store_dwordx4 v[98:99], v[80:83], off nt
	s_nop 1
	v_cvt_pk_bf16_f32 v80, v84, v85
	v_cvt_pk_bf16_f32 v81, v86, v87
	v_cvt_pk_bf16_f32 v82, v96, v97
	v_cvt_pk_bf16_f32 v83, v100, v101
	global_store_dwordx4 v[98:99], v[80:83], off offset:256 nt
	global_load_dword v80, v[146:147], off offset:192
	s_waitcnt vmcnt(0)
; __device__ __forceinline__ unsigned cvt_pk_bf16(float lo, float hi) { unsigned r; asm volatile("v_cvt_pk_bf16_f32 %0, %1, %2" : "=v"(r) : "v"(lo), "v"(hi)); return r; }
;     __device__ __forceinline__ void operator()(const f32x4 (&acc)[2][2][4][2], const Unit& u, int wr, int wc, int fr, int fq) const {
;     ...
;             for (int m = 0; m < 4; ++m) { const int row = row0 + ai * HALF + m * 16; const float rs = ACT == 1 ? ss[row] : 1.0f;
;                 bf16_t* rowp = O + (size_t)row * ldc + col0;
; #pragma unroll
;                 for (int bj = 0; bj < 2; ++bj) { f32x4 v0 = acc[ai][bj][m][0] * rs, v1 = acc[ai][bj][m][1] * rs;
;                     if (ACT == 1) {
; #pragma unroll
;                         for (int e = 0; e < 4; ++e) { const float a0 = fmaxf(v0[e], 0.f), a1 = fmaxf(v1[e], 0.f); v0[e] = a0 * a0; v1[e] = a1 * a1; } }
;                     u32x4 w; w.x = cvt_pk_bf16(v0[0], v0[1]); w.y = cvt_pk_bf16(v0[2], v0[3]); w.z = cvt_pk_bf16(v1[0], v1[1]); w.w = cvt_pk_bf16(v1[2], v1[3]);
;                     *(u32x4*)(rowp + bj * HALF) = w; } }
	v_pk_mul_f32 v[78:79], v[78:79], v[80:81] op_sel_hi:[1,0]
	v_or_b32_e32 v82, 48, v148
	v_ashrrev_i32_e32 v83, 31, v82
	v_lshlrev_b64 v[82:83], 14, v[82:83]
	v_pk_mul_f32 v[76:77], v[76:77], v[80:81] op_sel_hi:[1,0]
	v_pk_mul_f32 v[74:75], v[74:75], v[80:81] op_sel_hi:[1,0]
	v_pk_mul_f32 v[72:73], v[72:73], v[80:81] op_sel_hi:[1,0]
	v_pk_mul_f32 v[66:67], v[66:67], v[80:81] op_sel_hi:[1,0]
	v_pk_mul_f32 v[64:65], v[64:65], v[80:81] op_sel_hi:[1,0]
	v_lshl_add_u64 v[82:83], s[74:75], 0, v[82:83]
	v_pk_mul_f32 v[70:71], v[70:71], v[80:81] op_sel_hi:[1,0]
	v_pk_mul_f32 v[68:69], v[68:69], v[80:81] op_sel_hi:[1,0]
	v_max_f32_e32 v76, 0, v76
	v_max_f32_e32 v72, 0, v72
	v_max_f32_e32 v77, 0, v77
	v_max_f32_e32 v73, 0, v73
	v_max_f32_e32 v78, 0, v78
	v_max_f32_e32 v74, 0, v74
	v_max_f32_e32 v79, 0, v79
	v_max_f32_e32 v75, 0, v75
	v_max_f32_e32 v64, 0, v64
	v_max_f32_e32 v65, 0, v65
	v_max_f32_e32 v66, 0, v66
	v_max_f32_e32 v67, 0, v67
	v_lshl_add_u64 v[82:83], v[82:83], 0, v[150:151]
	v_max_f32_e32 v68, 0, v68
	v_max_f32_e32 v69, 0, v69
	v_max_f32_e32 v70, 0, v70
	v_max_f32_e32 v71, 0, v71
	v_mul_f32_e32 v76, v76, v76
	v_mul_f32_e32 v72, v72, v72
	v_mul_f32_e32 v77, v77, v77
	v_mul_f32_e32 v73, v73, v73
	v_mul_f32_e32 v78, v78, v78
	v_mul_f32_e32 v74, v74, v74
	v_mul_f32_e32 v79, v79, v79
	v_mul_f32_e32 v75, v75, v75
	v_mul_f32_e32 v80, v64, v64
	v_mul_f32_e32 v81, v65, v65
	v_mul_f32_e32 v84, v66, v66
	v_mul_f32_e32 v85, v67, v67
	v_cvt_pk_bf16_f32 v64, v76, v77
	v_cvt_pk_bf16_f32 v65, v78, v79
	v_cvt_pk_bf16_f32 v66, v72, v73
	v_cvt_pk_bf16_f32 v67, v74, v75
	v_mul_f32_e32 v68, v68, v68
	v_mul_f32_e32 v69, v69, v69
	v_mul_f32_e32 v70, v70, v70
	v_mul_f32_e32 v71, v71, v71
	global_store_dwordx4 v[82:83], v[64:67], off nt
	s_nop 1
	v_cvt_pk_bf16_f32 v64, v68, v69
	v_cvt_pk_bf16_f32 v65, v70, v71
	v_cvt_pk_bf16_f32 v66, v80, v81
	v_cvt_pk_bf16_f32 v67, v84, v85
	global_store_dwordx4 v[82:83], v[64:67], off offset:256 nt
	global_load_dword v64, v[146:147], off offset:512
	v_add_co_u32_e32 v68, vcc, s52, v144
	v_lshl_add_u64 v[66:67], v[144:145], 0, s[16:17]
	s_nop 0
	v_addc_co_u32_e32 v69, vcc, 0, v145, vcc
	s_waitcnt vmcnt(0)
	v_pk_mul_f32 v[62:63], v[62:63], v[64:65] op_sel_hi:[1,0]
	v_pk_mul_f32 v[60:61], v[60:61], v[64:65] op_sel_hi:[1,0]
	v_pk_mul_f32 v[58:59], v[58:59], v[64:65] op_sel_hi:[1,0]
	v_pk_mul_f32 v[56:57], v[56:57], v[64:65] op_sel_hi:[1,0]
	v_pk_mul_f32 v[50:51], v[50:51], v[64:65] op_sel_hi:[1,0]
	v_pk_mul_f32 v[48:49], v[48:49], v[64:65] op_sel_hi:[1,0]
	v_pk_mul_f32 v[54:55], v[54:55], v[64:65] op_sel_hi:[1,0]
	v_pk_mul_f32 v[52:53], v[52:53], v[64:65] op_sel_hi:[1,0]
	v_max_f32_e32 v60, 0, v60
	v_max_f32_e32 v56, 0, v56
	v_max_f32_e32 v61, 0, v61
	v_max_f32_e32 v57, 0, v57
	v_max_f32_e32 v62, 0, v62
	v_max_f32_e32 v58, 0, v58
	v_max_f32_e32 v63, 0, v63
	v_max_f32_e32 v59, 0, v59
	v_max_f32_e32 v48, 0, v48
	v_max_f32_e32 v49, 0, v49
	v_max_f32_e32 v50, 0, v50
	v_max_f32_e32 v51, 0, v51
	v_max_f32_e32 v52, 0, v52
	v_max_f32_e32 v53, 0, v53
	v_max_f32_e32 v54, 0, v54
	v_max_f32_e32 v55, 0, v55
	v_mul_f32_e32 v60, v60, v60
	v_mul_f32_e32 v56, v56, v56
	v_mul_f32_e32 v61, v61, v61
	v_mul_f32_e32 v57, v57, v57
	v_mul_f32_e32 v62, v62, v62
	v_mul_f32_e32 v58, v58, v58
	v_mul_f32_e32 v63, v63, v63
	v_mul_f32_e32 v59, v59, v59
	v_mul_f32_e32 v64, v48, v48
	v_mul_f32_e32 v65, v49, v49
	v_mul_f32_e32 v70, v50, v50
	v_mul_f32_e32 v71, v51, v51
	v_cvt_pk_bf16_f32 v48, v60, v61
	v_cvt_pk_bf16_f32 v49, v62, v63
	v_cvt_pk_bf16_f32 v50, v56, v57
	v_cvt_pk_bf16_f32 v51, v58, v59
	v_mul_f32_e32 v52, v52, v52
	v_mul_f32_e32 v53, v53, v53
	v_mul_f32_e32 v54, v54, v54
	v_mul_f32_e32 v55, v55, v55
	global_store_dwordx4 v[68:69], v[48:51], off nt
	s_nop 1
	v_cvt_pk_bf16_f32 v48, v52, v53
	v_cvt_pk_bf16_f32 v49, v54, v55
	v_cvt_pk_bf16_f32 v50, v64, v65
	v_cvt_pk_bf16_f32 v51, v70, v71
	global_store_dwordx4 v[66:67], v[48:51], off offset:256 nt
	global_load_dword v48, v[146:147], off offset:576
	v_add_co_u32_e32 v52, vcc, s53, v144
	v_lshl_add_u64 v[50:51], v[144:145], 0, s[18:19]
	s_nop 0
	v_addc_co_u32_e32 v53, vcc, 0, v145, vcc
	s_waitcnt vmcnt(0)
; __device__ __forceinline__ unsigned cvt_pk_bf16(float lo, float hi) { unsigned r; asm volatile("v_cvt_pk_bf16_f32 %0, %1, %2" : "=v"(r) : "v"(lo), "v"(hi)); return r; }
;     __device__ __forceinline__ void operator()(const f32x4 (&acc)[2][2][4][2], const Unit& u, int wr, int wc, int fr, int fq) const {
;     ...
;             for (int m = 0; m < 4; ++m) { const int row = row0 + ai * HALF + m * 16; const float rs = ACT == 1 ? ss[row] : 1.0f;
;                 bf16_t* rowp = O + (size_t)row * ldc + col0;
; #pragma unroll
;                 for (int bj = 0; bj < 2; ++bj) { f32x4 v0 = acc[ai][bj][m][0] * rs, v1 = acc[ai][bj][m][1] * rs;
;                     if (ACT == 1) {
; #pragma unroll
;                         for (int e = 0; e < 4; ++e) { const float a0 = fmaxf(v0[e], 0.f), a1 = fmaxf(v1[e], 0.f); v0[e] = a0 * a0; v1[e] = a1 * a1; } }
;                     u32x4 w; w.x = cvt_pk_bf16(v0[0], v0[1]); w.y = cvt_pk_bf16(v0[2], v0[3]); w.z = cvt_pk_bf16(v1[0], v1[1]); w.w = cvt_pk_bf16(v1[2], v1[3]);
;                     *(u32x4*)(rowp + bj * HALF) = w; } }
	v_pk_mul_f32 v[46:47], v[46:47], v[48:49] op_sel_hi:[1,0]
	v_pk_mul_f32 v[44:45], v[44:45], v[48:49] op_sel_hi:[1,0]
	v_pk_mul_f32 v[42:43], v[42:43], v[48:49] op_sel_hi:[1,0]
	v_pk_mul_f32 v[40:41], v[40:41], v[48:49] op_sel_hi:[1,0]
	v_pk_mul_f32 v[34:35], v[34:35], v[48:49] op_sel_hi:[1,0]
	v_pk_mul_f32 v[32:33], v[32:33], v[48:49] op_sel_hi:[1,0]
	v_pk_mul_f32 v[38:39], v[38:39], v[48:49] op_sel_hi:[1,0]
	v_pk_mul_f32 v[36:37], v[36:37], v[48:49] op_sel_hi:[1,0]
	v_max_f32_e32 v44, 0, v44
	v_max_f32_e32 v40, 0, v40
	v_max_f32_e32 v45, 0, v45
	v_max_f32_e32 v41, 0, v41
	v_max_f32_e32 v46, 0, v46
	v_max_f32_e32 v42, 0, v42
	v_max_f32_e32 v47, 0, v47
	v_max_f32_e32 v43, 0, v43
	v_max_f32_e32 v32, 0, v32
	v_max_f32_e32 v33, 0, v33
	v_max_f32_e32 v34, 0, v34
	v_max_f32_e32 v35, 0, v35
	v_max_f32_e32 v36, 0, v36
	v_max_f32_e32 v37, 0, v37
	v_max_f32_e32 v38, 0, v38
	v_max_f32_e32 v39, 0, v39
	v_mul_f32_e32 v44, v44, v44
	v_mul_f32_e32 v40, v40, v40
	v_mul_f32_e32 v45, v45, v45
	v_mul_f32_e32 v41, v41, v41
	v_mul_f32_e32 v46, v46, v46
	v_mul_f32_e32 v42, v42, v42
	v_mul_f32_e32 v47, v47, v47
	v_mul_f32_e32 v43, v43, v43
	v_mul_f32_e32 v48, v32, v32
	v_mul_f32_e32 v49, v33, v33
	v_mul_f32_e32 v54, v34, v34
	v_mul_f32_e32 v55, v35, v35
	v_cvt_pk_bf16_f32 v32, v44, v45
	v_cvt_pk_bf16_f32 v33, v46, v47
	v_cvt_pk_bf16_f32 v34, v40, v41
	v_cvt_pk_bf16_f32 v35, v42, v43
	v_mul_f32_e32 v36, v36, v36
	v_mul_f32_e32 v37, v37, v37
	v_mul_f32_e32 v38, v38, v38
	v_mul_f32_e32 v39, v39, v39
	global_store_dwordx4 v[52:53], v[32:35], off nt
	s_nop 1
	v_cvt_pk_bf16_f32 v32, v36, v37
	v_cvt_pk_bf16_f32 v33, v38, v39
	v_cvt_pk_bf16_f32 v34, v48, v49
	v_cvt_pk_bf16_f32 v35, v54, v55
	global_store_dwordx4 v[50:51], v[32:35], off offset:256 nt
	global_load_dword v32, v[146:147], off offset:640
	v_add_co_u32_e32 v36, vcc, s54, v144
	v_lshl_add_u64 v[34:35], v[144:145], 0, s[20:21]
	s_nop 0
	v_addc_co_u32_e32 v37, vcc, 0, v145, vcc
	s_andn2_b64 vcc, exec, s[4:5]
	s_waitcnt vmcnt(0)
	v_pk_mul_f32 v[30:31], v[30:31], v[32:33] op_sel_hi:[1,0]
	v_pk_mul_f32 v[28:29], v[28:29], v[32:33] op_sel_hi:[1,0]
	v_pk_mul_f32 v[26:27], v[26:27], v[32:33] op_sel_hi:[1,0]
	v_pk_mul_f32 v[24:25], v[24:25], v[32:33] op_sel_hi:[1,0]
	v_pk_mul_f32 v[18:19], v[18:19], v[32:33] op_sel_hi:[1,0]
	v_pk_mul_f32 v[16:17], v[16:17], v[32:33] op_sel_hi:[1,0]
	v_pk_mul_f32 v[22:23], v[22:23], v[32:33] op_sel_hi:[1,0]
	v_pk_mul_f32 v[20:21], v[20:21], v[32:33] op_sel_hi:[1,0]
	v_max_f32_e32 v28, 0, v28
	v_max_f32_e32 v24, 0, v24
	v_max_f32_e32 v29, 0, v29
	v_max_f32_e32 v25, 0, v25
	v_max_f32_e32 v30, 0, v30
	v_max_f32_e32 v26, 0, v26
	v_max_f32_e32 v31, 0, v31
	v_max_f32_e32 v27, 0, v27
	v_max_f32_e32 v16, 0, v16
	v_max_f32_e32 v17, 0, v17
	v_max_f32_e32 v18, 0, v18
	v_max_f32_e32 v19, 0, v19
	v_max_f32_e32 v20, 0, v20
	v_max_f32_e32 v21, 0, v21
	v_max_f32_e32 v22, 0, v22
	v_max_f32_e32 v23, 0, v23
	v_mul_f32_e32 v28, v28, v28
	v_mul_f32_e32 v24, v24, v24
	v_mul_f32_e32 v29, v29, v29
	v_mul_f32_e32 v25, v25, v25
	v_mul_f32_e32 v30, v30, v30
	v_mul_f32_e32 v26, v26, v26
	v_mul_f32_e32 v31, v31, v31
	v_mul_f32_e32 v27, v27, v27
	v_mul_f32_e32 v32, v16, v16
	v_mul_f32_e32 v33, v17, v17
	v_mul_f32_e32 v38, v18, v18
	v_mul_f32_e32 v39, v19, v19
	v_cvt_pk_bf16_f32 v16, v28, v29
	v_cvt_pk_bf16_f32 v17, v30, v31
	v_cvt_pk_bf16_f32 v18, v24, v25
	v_cvt_pk_bf16_f32 v19, v26, v27
	v_mul_f32_e32 v20, v20, v20
	v_mul_f32_e32 v21, v21, v21
	v_mul_f32_e32 v22, v22, v22
	v_mul_f32_e32 v23, v23, v23
	global_store_dwordx4 v[36:37], v[16:19], off nt
	s_nop 1
	v_cvt_pk_bf16_f32 v16, v20, v21
	v_cvt_pk_bf16_f32 v17, v22, v23
	v_cvt_pk_bf16_f32 v18, v32, v33
	v_cvt_pk_bf16_f32 v19, v38, v39
	global_store_dwordx4 v[34:35], v[16:19], off offset:256 nt
	global_load_dword v16, v[146:147], off offset:704
	v_add_co_u32_e64 v20, s[0:1], s55, v144
	v_lshl_add_u64 v[18:19], v[144:145], 0, s[22:23]
	s_nop 0
	v_addc_co_u32_e64 v21, s[0:1], 0, v145, s[0:1]
	s_mov_b64 s[0:1], -1
	s_waitcnt vmcnt(0)
	v_pk_mul_f32 v[14:15], v[14:15], v[16:17] op_sel_hi:[1,0]
	v_pk_mul_f32 v[12:13], v[12:13], v[16:17] op_sel_hi:[1,0]
	v_pk_mul_f32 v[10:11], v[10:11], v[16:17] op_sel_hi:[1,0]
	v_pk_mul_f32 v[8:9], v[8:9], v[16:17] op_sel_hi:[1,0]
	v_pk_mul_f32 v[2:3], v[2:3], v[16:17] op_sel_hi:[1,0]
	v_pk_mul_f32 v[0:1], v[0:1], v[16:17] op_sel_hi:[1,0]
	v_pk_mul_f32 v[6:7], v[6:7], v[16:17] op_sel_hi:[1,0]
	v_pk_mul_f32 v[4:5], v[4:5], v[16:17] op_sel_hi:[1,0]
	v_max_f32_e32 v12, 0, v12
	v_max_f32_e32 v8, 0, v8
	v_max_f32_e32 v13, 0, v13
	v_max_f32_e32 v9, 0, v9
	v_max_f32_e32 v14, 0, v14
	v_max_f32_e32 v10, 0, v10
	v_max_f32_e32 v15, 0, v15
	v_max_f32_e32 v11, 0, v11
	v_max_f32_e32 v0, 0, v0
	v_max_f32_e32 v1, 0, v1
	v_max_f32_e32 v2, 0, v2
	v_max_f32_e32 v3, 0, v3
	v_max_f32_e32 v4, 0, v4
	v_max_f32_e32 v5, 0, v5
	v_max_f32_e32 v6, 0, v6
	v_max_f32_e32 v7, 0, v7
	v_mul_f32_e32 v12, v12, v12
	v_mul_f32_e32 v8, v8, v8
	v_mul_f32_e32 v13, v13, v13
	v_mul_f32_e32 v9, v9, v9
	v_mul_f32_e32 v14, v14, v14
	v_mul_f32_e32 v10, v10, v10
	v_mul_f32_e32 v15, v15, v15
	v_mul_f32_e32 v11, v11, v11
	v_mul_f32_e32 v16, v0, v0
	v_mul_f32_e32 v17, v1, v1
	v_mul_f32_e32 v22, v2, v2
	v_mul_f32_e32 v23, v3, v3
	v_cvt_pk_bf16_f32 v0, v12, v13
	v_cvt_pk_bf16_f32 v1, v14, v15
	v_cvt_pk_bf16_f32 v2, v8, v9
	v_cvt_pk_bf16_f32 v3, v10, v11
	v_mul_f32_e32 v4, v4, v4
	v_mul_f32_e32 v5, v5, v5
	v_mul_f32_e32 v6, v6, v6
	v_mul_f32_e32 v7, v7, v7
	global_store_dwordx4 v[20:21], v[0:3], off nt
	s_nop 1
	v_cvt_pk_bf16_f32 v0, v4, v5
	v_cvt_pk_bf16_f32 v1, v6, v7
	v_cvt_pk_bf16_f32 v2, v16, v17
	v_cvt_pk_bf16_f32 v3, v22, v23
	global_store_dwordx4 v[18:19], v[0:3], off offset:256 nt
	s_cbranch_vccnz .LBB0_929
	s_andn2_b64 vcc, exec, s[8:9]
	s_cbranch_vccnz .LBB0_928
	s_barrier
	s_branch .LBB0_928
